# post phase: halo/conv-carry copy loops issue their 12 loads at once; kv-gain and kr loads hoisted
# speedup vs baseline: 1.0322x; 1.0312x over previous
; DI unsigned pk2(float lo, float hi) { f32x2 v = {lo, hi}; bf16x2_t b = __builtin_convertvector(v, bf16x2_t); return __builtin_bit_cast(unsigned, b); }
; DI float bflo(unsigned u) { return __uint_as_float(u << 16); }
; DI float bfhi(unsigned u) { return __uint_as_float(u & 0xffff0000u); }
; DI void phase_post(const Prm& p, int gw, int ngw, int lane) {
;     ...
;         { unsigned* q = (unsigned*)(row + C_CQ); unsigned u[3]; float ss = 0.f;
; #pragma unroll
;           for (int j = 0; j < 3; ++j) { u[j] = q[lane + 64 * j]; const float a = bflo(u[j]), b = bfhi(u[j]); ss += a * a + b * b; }
;           ss = wave_sum(ss); const float rstd = rsqrtf(ss * (1.f / 384.f) + 1e-6f);
; #pragma unroll
;           for (int j = 0; j < 3; ++j) { const int c = 2 * (lane + 64 * j); q[lane + 64 * j] = pk2(bflo(u[j]) * rstd * p.q_norm[c], bfhi(u[j]) * rstd * p.q_norm[c + 1]); } }
;         { u32x2* q = (u32x2*)(row + C_CKV) + lane; const u32x2 u = *q; float v[4] = {bflo(u.x), bfhi(u.x), bflo(u.y), bfhi(u.y)};
;           float ss = v[0] * v[0] + v[1] * v[1] + v[2] * v[2] + v[3] * v[3]; ss = wave_sum(ss); const float rstd = rsqrtf(ss * (1.f / 256.f) + 1e-6f);
;           const f32x4 g = ((const f32x4*)p.kv_norm)[lane]; f32x4 c = {v[0] * rstd * g.x, v[1] * rstd * g.y, v[2] * rstd * g.z, v[3] * rstd * g.w};
;           ((f32x4*)ockv)[lane] = c; u32x2 w; w.x = pk2(c.x, c.y); w.y = pk2(c.z, c.w); *q = w; }
;         if (lane < 32) { unsigned* q = (unsigned*)(row + C_KR) + lane; const unsigned u = *q; const float x1 = bflo(u), x2 = bfhi(u); const float* tb = tbl + (size_t)rowpos(r) * 64; const float c = tb[lane], s = tb[32 + lane];
;             const float o1 = x1 * c - x2 * s, o2 = x2 * c + x1 * s; okr[lane] = o1; okr[32 + lane] = o2; const unsigned w = pk2(o1, o2); *q = w; }
.LBB0_975:
	s_mul_i32 s36, s2, 0x1600
	v_readlane_b32 s38, v247, 62
	s_mul_hi_i32 s0, s2, 0x1600
	v_readlane_b32 s39, v247, 63
	s_add_u32 s38, s38, s36
	s_addc_u32 s39, s39, s0
	s_add_u32 s0, s30, s16
	s_addc_u32 s36, s31, s17
	s_lshl_b64 s[16:17], s[24:25], 10
	s_add_u32 s40, s0, s16
	s_addc_u32 s41, s36, s17
	s_add_u32 s44, s38, 0x1000
	s_addc_u32 s45, s39, 0
	global_load_dword v58, v0, s[44:45]
	global_load_dword v59, v28, s[44:45]
	global_load_dword v60, v29, s[44:45]
	global_load_dword v245, v0, s[44:45] offset:1280
	v_lshl_add_u64 v[24:25], s[38:39], 0, v[20:21]
	v_add_co_u32_e32 v34, vcc, s33, v24
	s_waitcnt vmcnt(2)
	v_and_b32_e32 v41, 0xffff0000, v58
	v_addc_co_u32_e32 v35, vcc, 0, v25, vcc
	global_load_dwordx2 v[62:63], v[34:35], off offset:768
	global_load_dwordx2 v[64:65], v[2:3], off
	global_load_dwordx2 v[66:67], v[4:5], off
	global_load_dwordx2 v[68:69], v[6:7], off
	global_load_dwordx4 v[72:75], v[8:9], off
	s_waitcnt vmcnt(5)
	v_lshlrev_b32_e32 v44, 16, v60
	v_and_b32_e32 v45, 0xffff0000, v60
	v_lshlrev_b32_e32 v40, 16, v58
	v_lshlrev_b32_e32 v42, 16, v59
	v_and_b32_e32 v43, 0xffff0000, v59
	v_mov_b32_e32 v52, v41
	v_mov_b32_e32 v53, v45
	v_mov_b32_e32 v50, v40
	v_mov_b32_e32 v51, v44
	v_pk_mul_f32 v[52:53], v[52:53], v[52:53]
	s_waitcnt vmcnt(4)
	v_lshlrev_b32_e32 v46, 16, v62
	v_and_b32_e32 v47, 0xffff0000, v62
	v_lshlrev_b32_e32 v48, 16, v63
	v_and_b32_e32 v49, 0xffff0000, v63
	v_pk_mul_f32 v[24:25], v[42:43], v[42:43]
	v_pk_mul_f32 v[54:55], v[46:47], v[46:47]
	v_pk_mul_f32 v[56:57], v[48:49], v[48:49]
	v_add_f32_e32 v33, v24, v25
	v_add_f32_e32 v54, v54, v55
	v_pk_fma_f32 v[24:25], v[50:51], v[50:51], v[52:53]
	v_add_f32_e32 v50, v56, v54
	v_add_f32_e32 v24, v24, v33
	v_add_f32_e32 v33, v57, v50
	v_add_f32_e32 v24, v24, v25
	s_nop 0
	v_add_f32_dpp v25, v33, v33 quad_perm:[1,0,3,2] row_mask:0xf bank_mask:0xf bound_ctrl:1
	v_add_f32_dpp v24, v24, v24 quad_perm:[1,0,3,2] row_mask:0xf bank_mask:0xf bound_ctrl:1
	s_nop 0
	v_add_f32_dpp v25, v25, v25 quad_perm:[2,3,0,1] row_mask:0xf bank_mask:0xf bound_ctrl:1
	v_add_f32_dpp v24, v24, v24 quad_perm:[2,3,0,1] row_mask:0xf bank_mask:0xf bound_ctrl:1
	s_nop 0
	v_add_f32_dpp v25, v25, v25 row_half_mirror row_mask:0xf bank_mask:0xf bound_ctrl:1
	v_add_f32_dpp v24, v24, v24 row_half_mirror row_mask:0xf bank_mask:0xf bound_ctrl:1
	s_nop 0
	v_add_f32_dpp v25, v25, v25 row_mirror row_mask:0xf bank_mask:0xf bound_ctrl:1
	v_add_f32_dpp v24, v24, v24 row_mirror row_mask:0xf bank_mask:0xf bound_ctrl:1
	v_readlane_b32 s0, v25, 16
	v_readlane_b32 s47, v25, 48
	v_readlane_b32 s48, v24, 16
	v_readlane_b32 s49, v24, 48
	v_readlane_b32 s16, v25, 0
	v_readlane_b32 s17, v25, 32
	v_readlane_b32 s36, v24, 0
	v_readlane_b32 s37, v24, 32
	v_mov_b32_e32 v24, s0
	v_mov_b32_e32 v25, s47
	v_mov_b32_e32 v50, s48
	v_mov_b32_e32 v51, s49
	v_pk_add_f32 v[24:25], s[16:17], v[24:25]
	v_pk_add_f32 v[50:51], s[36:37], v[50:51]
	v_mov_b32_e32 v52, v24
	v_mov_b32_e32 v53, v50
	v_mov_b32_e32 v50, v25
	v_pk_add_f32 v[24:25], v[52:53], v[50:51]
	s_nop 0
	v_pk_fma_f32 v[50:51], v[24:25], s[6:7], v[22:23] op_sel_hi:[1,1,0]
	s_nop 0
	v_mul_f32_e32 v24, 0x4b800000, v51
	v_cmp_gt_f32_e32 vcc, s42, v51
	v_mul_f32_e32 v33, 0x4b800000, v50
	s_nop 0
	v_cndmask_b32_e32 v24, v51, v24, vcc
	v_rsq_f32_e32 v24, v24
	s_nop 0
	v_mul_f32_e32 v25, 0x45800000, v24
	v_cndmask_b32_e32 v24, v24, v25, vcc
	v_pk_mul_f32 v[40:41], v[24:25], v[40:41] op_sel_hi:[0,1]
	v_pk_mul_f32 v[42:43], v[24:25], v[42:43] op_sel_hi:[0,1]
	v_pk_mul_f32 v[24:25], v[24:25], v[44:45] op_sel_hi:[0,1]
	s_waitcnt vmcnt(3)
	v_pk_mul_f32 v[26:27], v[64:65], v[40:41]
	s_waitcnt vmcnt(2)
	v_pk_mul_f32 v[36:37], v[66:67], v[42:43]
	s_waitcnt vmcnt(1)
	v_pk_mul_f32 v[24:25], v[68:69], v[24:25]
	v_cvt_pk_bf16_f32 v26, v26, v27
	v_cvt_pk_bf16_f32 v27, v36, v37
	v_cvt_pk_bf16_f32 v24, v24, v25
	global_store_dword v0, v26, s[44:45]
	global_store_dword v28, v27, s[44:45]
	global_store_dword v29, v24, s[44:45]
	s_nop 0
	v_cmp_gt_f32_e32 vcc, s42, v50
	s_nop 1
	v_cndmask_b32_e32 v33, v50, v33, vcc
	v_rsq_f32_e32 v33, v33
	s_nop 0
	v_mul_f32_e32 v36, 0x45800000, v33
	v_cndmask_b32_e32 v36, v33, v36, vcc
	v_pk_mul_f32 v[38:39], v[36:37], v[46:47] op_sel_hi:[0,1]
	v_pk_mul_f32 v[36:37], v[36:37], v[48:49] op_sel_hi:[0,1]
	s_waitcnt vmcnt(3)
	v_pk_mul_f32 v[24:25], v[72:73], v[38:39]
	v_pk_mul_f32 v[26:27], v[74:75], v[36:37]
	global_store_dwordx4 v30, v[24:27], s[40:41]
	s_nop 1
	v_cvt_pk_bf16_f32 v24, v24, v25
	v_cvt_pk_bf16_f32 v25, v26, v27
	global_store_dwordx2 v[34:35], v[24:25], off offset:768
	s_and_saveexec_b64 s[16:17], s[4:5]
	s_cbranch_execz .LBB0_985
	v_lshl_add_u64 v[24:25], s[38:39], 0, v[0:1]
	v_add_co_u32_e32 v26, vcc, 0x1000, v24
	s_mov_b64 s[36:37], -1
	s_nop 0
	v_addc_co_u32_e32 v27, vcc, 0, v25, vcc
	s_nop 0
	s_and_b64 vcc, exec, s[20:21]
	s_cbranch_vccz .LBB0_982
	s_cmpk_gt_u32 s2, 0x87ff
	s_cbranch_scc0 .LBB0_979
	s_and_b32 s0, s2, 15
	s_mov_b64 s[36:37], 0

; DI unsigned pk2(float lo, float hi) { f32x2 v = {lo, hi}; bf16x2_t b = __builtin_convertvector(v, bf16x2_t); return __builtin_bit_cast(unsigned, b); }
; DI float bflo(unsigned u) { return __uint_as_float(u << 16); }
; DI float bfhi(unsigned u) { return __uint_as_float(u & 0xffff0000u); }
; DI void phase_post(const Prm& p, int gw, int ngw, int lane) {
;     ...
;         if (lane < 32) { unsigned* q = (unsigned*)(row + C_KR) + lane; const unsigned u = *q; const float x1 = bflo(u), x2 = bfhi(u); const float* tb = tbl + (size_t)rowpos(r) * 64; const float c = tb[lane], s = tb[32 + lane];
;             const float o1 = x1 * c - x2 * s, o2 = x2 * c + x1 * s; okr[lane] = o1; okr[32 + lane] = o2; const unsigned w = pk2(o1, o2); *q = w; }
.LBB0_984:
	s_add_u32 s26, s30, s26
	s_addc_u32 s27, s31, s27
	s_lshl_b64 s[24:25], s[24:25], 8
	s_add_u32 s24, s26, s24
	s_addc_u32 s25, s27, s25
	s_lshl_b32 s0, s0, 6
	v_lshl_add_u64 v[34:35], s[0:1], 2, v[10:11]
	global_load_dword v36, v[34:35], off offset:128
	s_nop 0
	global_load_dword v34, v[34:35], off
	s_waitcnt vmcnt(2)
	v_lshlrev_b32_e32 v38, 16, v245
	v_and_b32_e32 v39, 0xffff0000, v245
	v_lshl_add_u64 v[24:25], v[24:25], 0, s[8:9]
	s_waitcnt vmcnt(1)
	v_pk_mul_f32 v[26:27], v[36:37], v[38:39] op_sel:[0,1] op_sel_hi:[0,0]
	s_waitcnt vmcnt(0)
	v_pk_fma_f32 v[36:37], v[34:35], v[38:39], v[26:27] op_sel_hi:[0,1,1] neg_lo:[0,0,1] neg_hi:[0,0,1]
	v_pk_fma_f32 v[26:27], v[34:35], v[38:39], v[26:27] op_sel_hi:[0,1,1]
	v_cvt_pk_bf16_f32 v26, v36, v27
	global_store_dword v0, v36, s[24:25]
	global_store_dword v0, v27, s[24:25] offset:128
	global_store_dword v[24:25], v26, off

; DI void phase_post(const Prm& p, int gw, int ngw, int lane) {
;     ...
;         { int hb = -1, hc = 0, hj = 0;
;           if (r < ROW_S) { const int t = r & 8191; if ((t & 63) >= 61 && t < 8128) { hb = r >> 13; hc = (t >> 6) + 2; hj = (t & 63) - 61; } }
;           else if (r >= ROW_META && ((r - ROW_META) & 15) >= 13) { hb = (r - ROW_META) >> 4; hc = 1; hj = ((r - ROW_META) & 15) - 13; }
;           if (hb >= 0) { unsigned* hd = (unsigned*)(halo + (((size_t)hb * 129 + hc) * 3 + hj) * 1536); for (int c = lane; c < 768; c += 64) hd[c] = ((const unsigned*)row)[c]; } }
.LBB0_996:
	global_load_dword v100, v[26:27], off
	global_load_dword v101, v[26:27], off offset:256
	global_load_dword v102, v[26:27], off offset:512
	global_load_dword v103, v[26:27], off offset:768
	global_load_dword v104, v[26:27], off offset:1024
	global_load_dword v105, v[26:27], off offset:1280
	global_load_dword v106, v[26:27], off offset:1536
	global_load_dword v107, v[26:27], off offset:1792
	global_load_dword v108, v[26:27], off offset:2048
	global_load_dword v109, v[26:27], off offset:2304
	global_load_dword v110, v[26:27], off offset:2560
	global_load_dword v111, v[26:27], off offset:2816
	s_waitcnt vmcnt(11)
	global_store_dword v[24:25], v100, off
	s_waitcnt vmcnt(11)
	global_store_dword v[24:25], v101, off offset:256
	s_waitcnt vmcnt(11)
	global_store_dword v[24:25], v102, off offset:512
	s_waitcnt vmcnt(11)
	global_store_dword v[24:25], v103, off offset:768
	s_waitcnt vmcnt(11)
	global_store_dword v[24:25], v104, off offset:1024
	s_waitcnt vmcnt(11)
	global_store_dword v[24:25], v105, off offset:1280
	s_waitcnt vmcnt(11)
	global_store_dword v[24:25], v106, off offset:1536
	s_waitcnt vmcnt(11)
	global_store_dword v[24:25], v107, off offset:1792
	s_waitcnt vmcnt(11)
	global_store_dword v[24:25], v108, off offset:2048
	s_waitcnt vmcnt(11)
	global_store_dword v[24:25], v109, off offset:2304
	s_waitcnt vmcnt(11)
	global_store_dword v[24:25], v110, off offset:2560
	s_waitcnt vmcnt(11)
	global_store_dword v[24:25], v111, off offset:2816
	s_or_b64 exec, exec, s[16:17]
	s_andn2_b64 vcc, exec, s[18:19]
	s_cbranch_vccnz .LBB0_1002

; DI float bflo(unsigned u) { return __uint_as_float(u << 16); }
; DI float bfhi(unsigned u) { return __uint_as_float(u & 0xffff0000u); }
; DI void phase_post(const Prm& p, int gw, int ngw, int lane) {
;     ...
;         if (r < ROW_S && (r & 8191) >= 8189) { float* o = p.out + O_PCONV + ((size_t)(r >> 13) * 3 + ((r & 8191) - 8189)) * 1536;
;             for (int c = lane; c < 768; c += 64) { const unsigned u = ((const unsigned*)row)[c]; o[2 * c] = bflo(u); o[2 * c + 1] = bfhi(u); } }
.LBB0_1000:
	global_load_dword v100, v[26:27], off
	global_load_dword v101, v[26:27], off offset:256
	global_load_dword v102, v[26:27], off offset:512
	global_load_dword v103, v[26:27], off offset:768
	global_load_dword v104, v[26:27], off offset:1024
	global_load_dword v105, v[26:27], off offset:1280
	global_load_dword v106, v[26:27], off offset:1536
	global_load_dword v107, v[26:27], off offset:1792
	global_load_dword v108, v[26:27], off offset:2048
	global_load_dword v109, v[26:27], off offset:2304
	global_load_dword v110, v[26:27], off offset:2560
	global_load_dword v111, v[26:27], off offset:2816
	s_waitcnt vmcnt(11)
	v_lshlrev_b32_e32 v34, 16, v100
	v_and_b32_e32 v35, 0xffff0000, v100
	global_store_dwordx2 v[24:25], v[34:35], off
	v_lshl_add_u64 v[24:25], v[24:25], 0, s[12:13]
	s_waitcnt vmcnt(11)
	v_lshlrev_b32_e32 v34, 16, v101
	v_and_b32_e32 v35, 0xffff0000, v101
	global_store_dwordx2 v[24:25], v[34:35], off
	v_lshl_add_u64 v[24:25], v[24:25], 0, s[12:13]
	s_waitcnt vmcnt(11)
	v_lshlrev_b32_e32 v34, 16, v102
	v_and_b32_e32 v35, 0xffff0000, v102
	global_store_dwordx2 v[24:25], v[34:35], off
	v_lshl_add_u64 v[24:25], v[24:25], 0, s[12:13]
	s_waitcnt vmcnt(11)
	v_lshlrev_b32_e32 v34, 16, v103
	v_and_b32_e32 v35, 0xffff0000, v103
	global_store_dwordx2 v[24:25], v[34:35], off
	v_lshl_add_u64 v[24:25], v[24:25], 0, s[12:13]
	s_waitcnt vmcnt(11)
	v_lshlrev_b32_e32 v34, 16, v104
	v_and_b32_e32 v35, 0xffff0000, v104
	global_store_dwordx2 v[24:25], v[34:35], off
	v_lshl_add_u64 v[24:25], v[24:25], 0, s[12:13]
	s_waitcnt vmcnt(11)
	v_lshlrev_b32_e32 v34, 16, v105
	v_and_b32_e32 v35, 0xffff0000, v105
	global_store_dwordx2 v[24:25], v[34:35], off
	v_lshl_add_u64 v[24:25], v[24:25], 0, s[12:13]
	s_waitcnt vmcnt(11)
	v_lshlrev_b32_e32 v34, 16, v106
	v_and_b32_e32 v35, 0xffff0000, v106
	global_store_dwordx2 v[24:25], v[34:35], off
	v_lshl_add_u64 v[24:25], v[24:25], 0, s[12:13]
	s_waitcnt vmcnt(11)
	v_lshlrev_b32_e32 v34, 16, v107
	v_and_b32_e32 v35, 0xffff0000, v107
	global_store_dwordx2 v[24:25], v[34:35], off
	v_lshl_add_u64 v[24:25], v[24:25], 0, s[12:13]
	s_waitcnt vmcnt(11)
	v_lshlrev_b32_e32 v34, 16, v108
	v_and_b32_e32 v35, 0xffff0000, v108
	global_store_dwordx2 v[24:25], v[34:35], off
	v_lshl_add_u64 v[24:25], v[24:25], 0, s[12:13]
	s_waitcnt vmcnt(11)
	v_lshlrev_b32_e32 v34, 16, v109
	v_and_b32_e32 v35, 0xffff0000, v109
	global_store_dwordx2 v[24:25], v[34:35], off
	v_lshl_add_u64 v[24:25], v[24:25], 0, s[12:13]
	s_waitcnt vmcnt(11)
	v_lshlrev_b32_e32 v34, 16, v110
	v_and_b32_e32 v35, 0xffff0000, v110
	global_store_dwordx2 v[24:25], v[34:35], off
	v_lshl_add_u64 v[24:25], v[24:25], 0, s[12:13]
	s_waitcnt vmcnt(11)
	v_lshlrev_b32_e32 v34, 16, v111
	v_and_b32_e32 v35, 0xffff0000, v111
	global_store_dwordx2 v[24:25], v[34:35], off
	v_lshl_add_u64 v[24:25], v[24:25], 0, s[12:13]
	s_or_b64 exec, exec, s[16:17]

; DI float bflo(unsigned u) { return __uint_as_float(u << 16); }
; DI float bfhi(unsigned u) { return __uint_as_float(u & 0xffff0000u); }
; DI void phase_post(const Prm& p, int gw, int ngw, int lane) {
;     ...
;         if (sidx >= 0 && (sidx & 63) >= 61) { float* o = p.out + O_SCONV + ((size_t)(sidx >> 6) * 3 + ((sidx & 63) - 61)) * 1536;
;             for (int c = lane; c < 768; c += 64) { const unsigned u = ((const unsigned*)row)[c]; o[2 * c] = bflo(u); o[2 * c + 1] = bfhi(u); } }
.LBB0_1005:
	global_load_dword v100, v[26:27], off
	global_load_dword v101, v[26:27], off offset:256
	global_load_dword v102, v[26:27], off offset:512
	global_load_dword v103, v[26:27], off offset:768
	global_load_dword v104, v[26:27], off offset:1024
	global_load_dword v105, v[26:27], off offset:1280
	global_load_dword v106, v[26:27], off offset:1536
	global_load_dword v107, v[26:27], off offset:1792
	global_load_dword v108, v[26:27], off offset:2048
	global_load_dword v109, v[26:27], off offset:2304
	global_load_dword v110, v[26:27], off offset:2560
	global_load_dword v111, v[26:27], off offset:2816
	s_waitcnt vmcnt(11)
	v_lshlrev_b32_e32 v34, 16, v100
	v_and_b32_e32 v35, 0xffff0000, v100
	global_store_dwordx2 v[24:25], v[34:35], off
	v_lshl_add_u64 v[24:25], v[24:25], 0, s[12:13]
	s_waitcnt vmcnt(11)
	v_lshlrev_b32_e32 v34, 16, v101
	v_and_b32_e32 v35, 0xffff0000, v101
	global_store_dwordx2 v[24:25], v[34:35], off
	v_lshl_add_u64 v[24:25], v[24:25], 0, s[12:13]
	s_waitcnt vmcnt(11)
	v_lshlrev_b32_e32 v34, 16, v102
	v_and_b32_e32 v35, 0xffff0000, v102
	global_store_dwordx2 v[24:25], v[34:35], off
	v_lshl_add_u64 v[24:25], v[24:25], 0, s[12:13]
	s_waitcnt vmcnt(11)
	v_lshlrev_b32_e32 v34, 16, v103
	v_and_b32_e32 v35, 0xffff0000, v103
	global_store_dwordx2 v[24:25], v[34:35], off
	v_lshl_add_u64 v[24:25], v[24:25], 0, s[12:13]
	s_waitcnt vmcnt(11)
	v_lshlrev_b32_e32 v34, 16, v104
	v_and_b32_e32 v35, 0xffff0000, v104
	global_store_dwordx2 v[24:25], v[34:35], off
	v_lshl_add_u64 v[24:25], v[24:25], 0, s[12:13]
	s_waitcnt vmcnt(11)
	v_lshlrev_b32_e32 v34, 16, v105
	v_and_b32_e32 v35, 0xffff0000, v105
	global_store_dwordx2 v[24:25], v[34:35], off
	v_lshl_add_u64 v[24:25], v[24:25], 0, s[12:13]
	s_waitcnt vmcnt(11)
	v_lshlrev_b32_e32 v34, 16, v106
	v_and_b32_e32 v35, 0xffff0000, v106
	global_store_dwordx2 v[24:25], v[34:35], off
	v_lshl_add_u64 v[24:25], v[24:25], 0, s[12:13]
	s_waitcnt vmcnt(11)
	v_lshlrev_b32_e32 v34, 16, v107
	v_and_b32_e32 v35, 0xffff0000, v107
	global_store_dwordx2 v[24:25], v[34:35], off
	v_lshl_add_u64 v[24:25], v[24:25], 0, s[12:13]
	s_waitcnt vmcnt(11)
	v_lshlrev_b32_e32 v34, 16, v108
	v_and_b32_e32 v35, 0xffff0000, v108
	global_store_dwordx2 v[24:25], v[34:35], off
	v_lshl_add_u64 v[24:25], v[24:25], 0, s[12:13]
	s_waitcnt vmcnt(11)
	v_lshlrev_b32_e32 v34, 16, v109
	v_and_b32_e32 v35, 0xffff0000, v109
	global_store_dwordx2 v[24:25], v[34:35], off
	v_lshl_add_u64 v[24:25], v[24:25], 0, s[12:13]
	s_waitcnt vmcnt(11)
	v_lshlrev_b32_e32 v34, 16, v110
	v_and_b32_e32 v35, 0xffff0000, v110
	global_store_dwordx2 v[24:25], v[34:35], off
	v_lshl_add_u64 v[24:25], v[24:25], 0, s[12:13]
	s_waitcnt vmcnt(11)
	v_lshlrev_b32_e32 v34, 16, v111
	v_and_b32_e32 v35, 0xffff0000, v111
	global_store_dwordx2 v[24:25], v[34:35], off
	v_lshl_add_u64 v[24:25], v[24:25], 0, s[12:13]
	s_or_b64 exec, exec, s[16:17]
	s_branch .LBB0_967
